# mamba chunk loop: dead zero-fills and dead loop-carried copies removed (22 VALU per chunk)
# baseline (speedup 1.0000x reference)
.LBB0_652:
	s_waitcnt lgkmcnt(0)
	s_cmpk_eq_i32 s24, 0x208
	s_mov_b32 s22, s24
	s_barrier
	s_cbranch_scc1 .LBB0_687
.LBB0_653:
	ds_read_b32 v0, v74 offset:34944
	ds_read_b64 v[2:3], v75 offset:32768
	s_add_i32 s24, s22, 1
	s_cmpk_lg_i32 s22, 0x207
	s_cselect_b64 s[18:19], -1, 0
	s_cmpk_eq_i32 s22, 0x207
	s_waitcnt lgkmcnt(0)
	v_pk_mul_f32 v[0:1], v[0:1], v[2:3] op_sel_hi:[0,1]
	ds_write_b64 v75, v[0:1] offset:32768
	s_waitcnt lgkmcnt(0)
	s_barrier
	s_cbranch_scc1 .LBB0_667
	v_sub_co_u32_e64 v0, s[20:21], s22, 7
	s_and_b64 s[26:27], s[20:21], exec
	v_readfirstlane_b32 s23, v0
	s_cselect_b32 s23, s24, s23
	s_cselect_b32 s25, 7, 0x1ff
	s_sub_i32 s25, s25, s23
	s_and_b64 s[26:27], s[40:41], exec
	s_cselect_b32 s23, s23, s25
	s_and_b64 s[20:21], s[20:21], exec
	s_cselect_b32 s20, 0x4000, 0
	s_lshl_b32 s23, s23, 5
	s_add_i32 s23, s23, s20
	s_and_saveexec_b64 s[20:21], s[4:5]
	s_cbranch_execz .LBB0_656
	v_add_u32_e32 v0, s23, v80
	v_mad_i64_i32 v[0:1], s[26:27], v0, s95, v[52:53]
	global_load_dwordx4 v[18:21], v[0:1], off
.LBB0_656:
	s_or_b64 exec, exec, s[20:21]
	s_and_saveexec_b64 s[20:21], s[6:7]
	s_cbranch_execz .LBB0_658
	v_add_u32_e32 v4, s23, v81
	v_mad_i64_i32 v[4:5], s[26:27], v4, s95, v[54:55]
	global_load_dwordx4 v[22:25], v[4:5], off
.LBB0_658:
	s_or_b64 exec, exec, s[20:21]
	s_and_saveexec_b64 s[20:21], s[8:9]
	s_cbranch_execz .LBB0_660
	v_add_u32_e32 v8, s23, v83
	v_mad_i64_i32 v[8:9], s[26:27], v8, s95, v[56:57]
	global_load_dwordx4 v[26:29], v[8:9], off
.LBB0_660:
	s_or_b64 exec, exec, s[20:21]
	s_and_saveexec_b64 s[20:21], s[10:11]
	s_cbranch_execz .LBB0_662
	v_add_u32_e32 v12, s23, v84
	v_mad_i64_i32 v[12:13], s[26:27], v12, s95, v[58:59]
	global_load_dwordx4 v[30:33], v[12:13], off
